# phase-3 queue: next ticket claimed before the item's final stores (parked in v255); loop head no longer drains stores or waits for the atomic
# baseline (speedup 1.0000x reference)
.LBB0_588:
	s_mov_b32 s98, 0
	v_mul_u32_u24_e32 v6, 0x13b2, v0
	v_mov_b32_e32 v7, 13
	v_mul_lo_u16_sdwa v7, v6, v7 dst_sel:DWORD dst_unused:UNUSED_PAD src0_sel:WORD_1 src1_sel:DWORD
	v_sub_u16_e32 v7, v0, v7
	v_min_u16_e32 v7, 11, v7
	s_movk_i32 s36, 0x60
	v_lshlrev_b16_e32 v8, 3, v7
	v_add_u32_e32 v7, 8, v188
	v_and_b32_e32 v5, 63, v0
	v_mul_lo_u16_sdwa v6, v6, s36 dst_sel:DWORD dst_unused:UNUSED_PAD src0_sel:WORD_1 src1_sel:DWORD
	v_lshlrev_b32_e32 v9, 6, v7
	s_mov_b32 s36, 0xffff
	v_or_b32_e32 v10, v9, v5
	v_bitop3_b32 v9, v9, s36, v5 bitop3:0xc8
	v_mul_u32_u24_e32 v9, 0x4ec5, v9
	v_lshrrev_b32_e32 v9, 18, v9
	v_mul_lo_u16_e32 v11, 13, v9
	v_sub_u16_e32 v10, v10, v11
	v_mul_hi_u32_u24_e32 v163, 0xc0, v9
	v_mul_u32_u24_e32 v162, 0xc0, v9
	v_min_u16_e32 v9, 11, v10
	v_lshlrev_b16_e32 v10, 3, v9
	v_mul_u32_u24_e32 v9, 0xf0f1, v5
	v_lshrrev_b32_e32 v9, 20, v9
	v_mul_lo_u16_e32 v11, 17, v9
	v_sub_u16_e32 v11, v5, v11
	v_lshlrev_b32_e32 v246, 10, v7
	v_or_b32_e32 v7, 16, v188
	v_lshlrev_b32_e32 v164, 13, v9
	v_min_u16_e32 v9, 15, v11
	v_lshlrev_b16_e32 v12, 3, v9
	v_lshlrev_b32_e32 v9, 6, v7
	v_or_b32_e32 v11, v9, v5
	v_bitop3_b32 v9, v9, s36, v5 bitop3:0xc8
	v_mul_u32_u24_e32 v9, 0x4ec5, v9
	v_lshrrev_b32_e32 v9, 18, v9
	v_mul_lo_u16_e32 v13, 13, v9
	v_sub_u16_e32 v11, v11, v13
	v_mul_lo_u16_e32 v14, 0x60, v9
	v_min_u16_e32 v9, 11, v11
	v_add_u32_e32 v11, -2, v188
	v_lshl_or_b32 v13, v11, 6, v5
	s_mov_b32 s37, 0x78787879
	v_mul_hi_u32 v15, v13, s37
	v_lshrrev_b32_e32 v18, 3, v15
	v_lshl_add_u32 v15, v18, 4, v18
	v_mov_b32_e32 v3, 0
	v_sub_u32_e32 v13, v13, v15
	v_mov_b32_e32 v19, v3
	v_min_u32_e32 v13, 15, v13
	v_lshlrev_b64 v[166:167], 13, v[18:19]
	v_lshlrev_b32_e32 v18, 3, v13
	v_mov_b32_e32 v13, 0x6800
	v_lshl_add_u32 v11, v11, 10, v13
	v_or_b32_e32 v13, 24, v188
	v_lshlrev_b32_e32 v15, 6, v13
	v_or_b32_e32 v17, v15, v5
	v_bitop3_b32 v15, v15, s36, v5 bitop3:0xc8
	v_mul_u32_u24_e32 v15, 0x4ec5, v15
	v_lshrrev_b32_e32 v15, 18, v15
	s_add_u32 s0, s62, 0x1200000
	v_mul_lo_u16_e32 v19, 13, v15
	s_addc_u32 s1, s63, 0
	v_lshlrev_b32_e32 v4, 2, v189
	v_sub_u16_e32 v17, v17, v19
	v_or_b32_e32 v2, 2, v4
	v_mul_hi_u32_u24_e32 v169, 0xc0, v15
	v_mul_u32_u24_e32 v168, 0xc0, v15
	v_min_u16_e32 v15, 11, v17
	s_add_u32 s50, s62, 0x13800400
	v_cmp_gt_u32_e64 s[6:7], v2, v156
	v_or_b32_e32 v2, 3, v4
	v_lshlrev_b16_e32 v20, 3, v15
	v_add_u32_e32 v15, 6, v188
	s_addc_u32 s51, s63, 0
	v_cmp_gt_u32_e64 s[8:9], v2, v156
	v_or_b32_e32 v2, 8, v4
	v_lshlrev_b32_e32 v17, 6, v15
	s_add_u32 s52, s62, 0x15800400
	v_lshl_add_u64 v[26:27], v[160:161], 1, s[62:63]
	v_lshlrev_b32_e32 v28, 7, v156
	v_mov_b32_e32 v29, v3
	v_cmp_gt_u32_e64 s[10:11], v2, v156
	v_or_b32_e32 v2, 9, v4
	v_or_b32_e32 v19, v17, v5
	v_bitop3_b32 v17, v17, s36, v5 bitop3:0xc8
	s_addc_u32 s53, s63, 0
	v_lshl_add_u64 v[26:27], v[26:27], 0, v[28:29]
	s_mov_b64 s[54:55], 0xd800400
	v_cmp_gt_u32_e64 s[12:13], v2, v156
	v_or_b32_e32 v2, 10, v4
	v_mul_u32_u24_e32 v17, 0xf0f1, v17
	v_lshl_add_u64 v[178:179], v[26:27], 0, s[54:55]
	s_add_u32 s54, s62, 0xb800400
	v_writelane_b32 v254, s92, 1
	v_cmp_gt_u32_e64 s[14:15], v2, v156
	v_or_b32_e32 v2, 11, v4
	v_lshrrev_b32_e32 v17, 20, v17
	s_addc_u32 s55, s63, 0
	v_writelane_b32 v254, s90, 2
	v_cmp_gt_u32_e64 s[16:17], v2, v156
	v_or_b32_e32 v2, 16, v4
	v_mul_lo_u16_e32 v21, 17, v17
	s_add_u32 s56, s62, 0x11800400
	v_writelane_b32 v254, s91, 3
	v_cmp_gt_u32_e64 s[18:19], v2, v156
	v_or_b32_e32 v2, 17, v4
	v_sub_u16_e32 v19, v19, v21
	s_addc_u32 s57, s63, 0
	v_writelane_b32 v254, s89, 4
	v_cmp_gt_u32_e64 s[20:21], v2, v156
	v_or_b32_e32 v2, 18, v4
	v_lshlrev_b32_e32 v170, 13, v17
	v_min_u16_e32 v17, 15, v19
	v_lshlrev_b32_e32 v247, 10, v15
	v_add_u32_e32 v15, 14, v188
	s_add_u32 s87, s62, 0x1400400
	v_writelane_b32 v254, s88, 5
	v_cmp_gt_u32_e64 s[22:23], v2, v156
	v_or_b32_e32 v2, 19, v4
	v_lshlrev_b16_e32 v22, 3, v17
	v_lshlrev_b32_e32 v17, 6, v15
	s_addc_u32 s88, s63, 0
	v_cmp_gt_u32_e64 s[24:25], v2, v156
	v_or_b32_e32 v2, 24, v4
	v_or_b32_e32 v19, v17, v5
	v_bitop3_b32 v5, v17, s36, v5 bitop3:0xc8
	s_add_u32 s89, s62, 0x19800400
	v_cmp_gt_u32_e64 s[26:27], v2, v156
	v_or_b32_e32 v2, 25, v4
	v_mul_u32_u24_e32 v5, 0xf0f1, v5
	s_addc_u32 s91, s63, 0
	v_cmp_gt_u32_e64 s[28:29], v2, v156
	v_or_b32_e32 v2, 26, v4
	v_lshrrev_b32_e32 v5, 20, v5
	s_add_u32 s92, s62, 0x1c800400
	v_cmp_gt_u32_e64 s[30:31], v2, v156
	v_or_b32_e32 v2, 27, v4
	v_mul_lo_u16_e32 v17, 17, v5
	s_addc_u32 s93, s63, 0
	v_cmp_gt_u32_e64 s[34:35], v2, v156
	v_lshlrev_b32_e32 v2, 6, v156
	v_sub_u16_e32 v17, v19, v17
	s_add_u32 s66, s62, 0x9800400
	v_mov_b32_e32 v159, v3
	s_movk_i32 s42, 0x80
	v_lshlrev_b32_e32 v172, 13, v5
	v_min_u16_e32 v5, 15, v17
	s_addc_u32 s67, s63, 0
	v_lshl_add_u64 v[26:27], s[62:63], 0, v[2:3]
	s_movk_i32 s86, 0xc0
	v_lshlrev_b16_e32 v16, 3, v9
	v_lshlrev_b32_e32 v9, 10, v7
	v_lshlrev_b32_e32 v13, 10, v13
	v_lshlrev_b16_e32 v24, 3, v5
	v_lshlrev_b32_e32 v248, 10, v15
	s_movk_i32 s36, 0x2c0
	v_mov_b32_e32 v5, 0x80
	v_mov_b32_e32 v15, 0x3000
	v_cmp_gt_u32_e64 s[40:41], 26, v7
	v_cmp_gt_u32_e64 s[42:43], s42, v0
	s_add_u32 s68, s62, 0x5400400
	v_lshl_add_u64 v[26:27], v[26:27], 0, v[158:159]
	s_mov_b64 s[70:71], 0x17800400
	v_lshrrev_b32_e32 v175, 8, v0
	v_and_b32_e32 v177, 3, v188
	v_cmp_gt_u32_e64 s[2:3], v4, v156
	v_cmp_lt_u32_e64 s[4:5], v4, v156
	v_lshrrev_b32_e32 v244, 7, v0
	v_lshlrev_b32_e32 v245, 10, v188
	v_mov_b32_e32 v165, v3
	v_mov_b32_e32 v171, v3
	v_mov_b32_e32 v173, v3
	v_cmp_gt_u32_e64 s[36:37], s36, v0
	v_cmp_gt_u32_e64 s[38:39], s86, v0
	v_mul_u32_u24_e32 v249, 0xd0, v156
	v_mul_u32_u24_e32 v250, 0x110, v156
	v_cndmask_b32_e64 v174, v5, v15, s[40:41]
	s_mov_b32 s49, 0
	v_cndmask_b32_e64 v251, 0, v9, s[40:41]
	v_cndmask_b32_e64 v176, v5, v15, s[42:43]
	v_cndmask_b32_e64 v252, v11, v13, s[42:43]
	s_addc_u32 s69, s63, 0
	v_lshl_add_u64 v[180:181], v[26:27], 0, s[70:71]
	s_add_i32 s94, 0, 0x24000
	v_mov_b32_e32 v159, 0x358637bd
	v_lshlrev_b32_e32 v182, 1, v4
	v_lshlrev_b32_e32 v184, 1, v6
	v_lshlrev_b32_e32 v186, 1, v8
	v_lshlrev_b32_e32 v188, 1, v10
	v_lshlrev_b32_e32 v190, 1, v14
	v_lshlrev_b32_e32 v192, 1, v16
	v_lshlrev_b32_e32 v194, 1, v12
	v_lshlrev_b32_e32 v196, 1, v20
	v_lshlrev_b32_e32 v198, 1, v18
	v_lshlrev_b32_e32 v200, 1, v22
	s_mov_b64 s[70:71], 0x100
	v_lshlrev_b32_e32 v202, 1, v24
	s_mov_b64 s[72:73], 0x6000
	s_mov_b32 s95, 0x41000000
	s_and_saveexec_b64 s[100:101], s[44:45]
	v_mov_b32_e32 v255, 1
	global_atomic_add v255, v3, v255, s[0:1] sc0
	s_mov_b64 exec, s[100:101]
	s_waitcnt vmcnt(0)
	s_branch .LBB0_593

.LBB0_593:
	s_waitcnt vmcnt(8) lgkmcnt(0)
	s_barrier
	s_and_saveexec_b64 s[74:75], s[44:45]
	s_cbranch_execz .LBB0_597
	v_mov_b32_e32 v4, s94
	ds_write_b32 v4, v255

.LBB0_622:
	s_or_b64 exec, exec, s[74:75]
	v_lshl_add_u32 v2, s48, 1, v175
	v_lshlrev_b32_e32 v4, 2, v2
	s_movk_i32 s48, 0x7c
	v_and_or_b32 v24, v4, s48, v177
	v_ashrrev_i32_e32 v4, 8, v2
	v_ashrrev_i32_e32 v5, 31, v4
	v_lshlrev_b64 v[4:5], 12, v[4:5]
	v_ashrrev_i32_e32 v20, 5, v2
	v_lshl_or_b32 v2, v24, 5, v4
	v_or_b32_e32 v5, v5, v1
	v_or_b32_e32 v4, v2, v156
	v_lshlrev_b64 v[56:57], 10, v[4:5]
	v_lshlrev_b32_e32 v2, 7, v20
	v_and_b32_e32 v2, 0x380, v2
	v_lshlrev_b64 v[8:9], 1, v[160:161]
	v_mov_b32_e32 v183, v3
	v_lshl_add_u64 v[4:5], s[52:53], 0, v[56:57]
	v_lshl_add_u64 v[4:5], v[4:5], 0, v[2:3]
	v_lshl_add_u64 v[148:149], v[4:5], 0, v[8:9]
	v_lshl_add_u64 v[10:11], s[50:51], 0, v[56:57]
	v_lshl_add_u64 v[10:11], v[10:11], 0, v[2:3]
	v_lshl_add_u64 v[150:151], v[10:11], 0, v[8:9]
	v_lshl_add_u64 v[10:11], s[54:55], 0, v[56:57]
	v_lshl_add_u64 v[10:11], v[10:11], 0, v[2:3]
	v_lshl_add_u64 v[240:241], v[10:11], 0, v[182:183]
	v_lshl_add_u64 v[10:11], s[56:57], 0, v[56:57]
	v_lshl_add_u64 v[10:11], v[10:11], 0, v[2:3]
	v_lshl_add_u64 v[242:243], v[10:11], 0, v[182:183]
	v_ashrrev_i32_e32 v21, 31, v20
	v_lshlrev_b64 v[20:21], 7, v[20:21]
	v_or_b32_e32 v20, v20, v24
	v_lshlrev_b64 v[22:23], 12, v[20:21]
	v_lshl_add_u64 v[152:153], v[180:181], 0, v[22:23]
	v_lshlrev_b64 v[12:13], 13, v[20:21]
	v_lshl_add_u64 v[12:13], v[178:179], 0, v[12:13]
	v_add_co_u32_e32 v154, vcc, 0x1000, v12
	s_nop 1
	v_addc_co_u32_e32 v155, vcc, 0, v13, vcc
	s_mov_b64 s[74:75], 0
	s_mov_b32 s48, 0x800000
	s_barrier
	global_load_dwordx4 v[52:55], v[148:149], off
	global_load_dwordx4 v[68:71], v[150:151], off
	global_load_dwordx4 v[56:59], v[148:149], off offset:32
	global_load_dwordx4 v[72:75], v[150:151], off offset:32
	global_load_dwordx4 v[60:63], v[148:149], off offset:64
	global_load_dwordx4 v[76:79], v[150:151], off offset:64
	global_load_dwordx4 v[64:67], v[148:149], off offset:96
	global_load_dwordx4 v[80:83], v[150:151], off offset:96
	global_load_dwordx4 v[100:103], v[154:155], off offset:-4096
	global_load_dwordx4 v[104:107], v[154:155], off offset:-4064
	global_load_dwordx4 v[108:111], v[154:155], off offset:-4032
	global_load_dwordx4 v[112:115], v[154:155], off offset:-4000
	global_load_dwordx4 v[116:119], v[154:155], off
	global_load_dwordx4 v[120:123], v[154:155], off offset:32
	global_load_dwordx4 v[124:127], v[154:155], off offset:64
	global_load_dwordx4 v[128:131], v[154:155], off offset:96
	global_load_dwordx2 v[84:85], v[152:153], off
	global_load_dwordx2 v[86:87], v[152:153], off offset:16
	global_load_dwordx2 v[88:89], v[152:153], off offset:2048
	global_load_dwordx2 v[90:91], v[152:153], off offset:2064
	global_load_dwordx2 v[92:93], v[152:153], off offset:32
	global_load_dwordx2 v[94:95], v[152:153], off offset:48
	global_load_dwordx2 v[96:97], v[152:153], off offset:2080
	global_load_dwordx2 v[98:99], v[152:153], off offset:2096
	global_load_dwordx2 v[132:133], v[240:241], off
	global_load_dwordx2 v[134:135], v[240:241], off offset:16
	global_load_dwordx2 v[136:137], v[240:241], off offset:32
	global_load_dwordx2 v[138:139], v[240:241], off offset:48
	global_load_dwordx2 v[140:141], v[240:241], off offset:64
	global_load_dwordx2 v[142:143], v[240:241], off offset:80
	global_load_dwordx2 v[144:145], v[240:241], off offset:96
	global_load_dwordx2 v[146:147], v[240:241], off offset:112
	s_waitcnt vmcnt(24)
	v_mfma_f32_32x32x16_bf16 v[36:51], v[52:55], v[68:71], 0
	v_mfma_f32_32x32x16_bf16 v[36:51], v[56:59], v[72:75], v[36:51]
	v_mfma_f32_32x32x16_bf16 v[36:51], v[60:63], v[76:79], v[36:51]
	v_mfma_f32_32x32x16_bf16 v[36:51], v[64:67], v[80:83], v[36:51]
	s_waitcnt vmcnt(16)
	v_mfma_f32_32x32x16_bf16 v[20:35], v[100:103], v[68:71], 0
	v_mfma_f32_32x32x16_bf16 v[4:19], v[116:119], v[68:71], 0
	v_mfma_f32_32x32x16_bf16 v[20:35], v[104:107], v[72:75], v[20:35]
	v_mfma_f32_32x32x16_bf16 v[4:19], v[120:123], v[72:75], v[4:19]
	v_mfma_f32_32x32x16_bf16 v[20:35], v[108:111], v[76:79], v[20:35]
	v_mfma_f32_32x32x16_bf16 v[4:19], v[124:127], v[76:79], v[4:19]
	v_mfma_f32_32x32x16_bf16 v[20:35], v[112:115], v[80:83], v[20:35]
	v_mfma_f32_32x32x16_bf16 v[4:19], v[128:131], v[80:83], v[4:19]
	s_nop 2
	v_cndmask_b32_e64 v44, v44, 0, s[18:19]
	v_cndmask_b32_e64 v45, v45, 0, s[20:21]
	v_cndmask_b32_e64 v46, v46, 0, s[22:23]
	v_cndmask_b32_e64 v47, v47, 0, s[24:25]
	v_cndmask_b32_e64 v48, v48, 0, s[26:27]
	v_cndmask_b32_e64 v49, v49, 0, s[28:29]
	v_cndmask_b32_e64 v50, v50, 0, s[30:31]
	v_cndmask_b32_e64 v51, v51, 0, s[34:35]
	v_cndmask_b32_e64 v240, v36, 0, s[2:3]
	v_cndmask_b32_e64 v241, 0, v37, s[4:5]
	v_cndmask_b32_e64 v38, v38, 0, s[6:7]
	v_cndmask_b32_e64 v39, v39, 0, s[8:9]
	v_cndmask_b32_e64 v40, v40, 0, s[10:11]
	v_cndmask_b32_e64 v41, v41, 0, s[12:13]
	v_cndmask_b32_e64 v42, v42, 0, s[14:15]
	v_cndmask_b32_e64 v43, v43, 0, s[16:17]
	v_cndmask_b32_e64 v240, v240, v36, s[4:5]
	v_cvt_pk_bf16_f32 v36, v240, v241
	v_cvt_pk_bf16_f32 v37, v38, v39
	v_cvt_pk_bf16_f32 v38, v40, v41
	v_cvt_pk_bf16_f32 v39, v42, v43
	v_cvt_pk_bf16_f32 v44, v44, v45
	v_cvt_pk_bf16_f32 v45, v46, v47
	v_cvt_pk_bf16_f32 v46, v48, v49
	v_cvt_pk_bf16_f32 v47, v50, v51
	s_waitcnt vmcnt(8)
	v_mfma_f32_32x32x16_bf16 v[20:35], v[84:87], v[36:39], v[20:35]
	v_mfma_f32_32x32x16_bf16 v[4:19], v[88:91], v[36:39], v[4:19]
	v_mfma_f32_32x32x16_bf16 v[20:35], v[92:95], v[44:47], v[20:35]
	v_mfma_f32_32x32x16_bf16 v[4:19], v[96:99], v[44:47], v[4:19]
	s_waitcnt vmcnt(0)
	s_and_saveexec_b64 s[100:101], s[44:45]
	v_mov_b32_e32 v255, 1
	global_atomic_add v255, v3, v255, s[0:1] sc0
	s_mov_b64 exec, s[100:101]
	v_lshlrev_b32_e32 v52, 16, v132
	v_and_b32_e32 v53, 0xffff0000, v132
	v_lshlrev_b32_e32 v54, 16, v133
	v_and_b32_e32 v55, 0xffff0000, v133
	v_lshlrev_b32_e32 v56, 16, v134
	v_and_b32_e32 v57, 0xffff0000, v134
	v_lshlrev_b32_e32 v58, 16, v135
	v_and_b32_e32 v59, 0xffff0000, v135
	v_lshlrev_b32_e32 v60, 16, v136
	v_and_b32_e32 v61, 0xffff0000, v136
	v_lshlrev_b32_e32 v62, 16, v137
	v_and_b32_e32 v63, 0xffff0000, v137
	v_lshlrev_b32_e32 v64, 16, v138
	v_and_b32_e32 v65, 0xffff0000, v138
	v_lshlrev_b32_e32 v66, 16, v139
	v_and_b32_e32 v67, 0xffff0000, v139
	v_lshlrev_b32_e32 v68, 16, v140
	v_and_b32_e32 v69, 0xffff0000, v140
	v_lshlrev_b32_e32 v70, 16, v141
	v_and_b32_e32 v71, 0xffff0000, v141
	v_lshlrev_b32_e32 v72, 16, v142
	v_and_b32_e32 v73, 0xffff0000, v142
	v_lshlrev_b32_e32 v74, 16, v143
	v_and_b32_e32 v75, 0xffff0000, v143
	v_lshlrev_b32_e32 v76, 16, v144
	v_and_b32_e32 v77, 0xffff0000, v144
	v_lshlrev_b32_e32 v78, 16, v145
	v_and_b32_e32 v79, 0xffff0000, v145
	v_lshlrev_b32_e32 v80, 16, v146
	v_and_b32_e32 v81, 0xffff0000, v146
	v_lshlrev_b32_e32 v82, 16, v147
	v_and_b32_e32 v83, 0xffff0000, v147
	v_mul_f32_e32 v100, v4, v4
	v_mul_f32_e32 v101, v5, v5
	v_mul_f32_e32 v102, v6, v6
	v_mul_f32_e32 v103, v7, v7
	v_mul_f32_e32 v104, v8, v8
	v_mul_f32_e32 v105, v9, v9
	v_mul_f32_e32 v106, v10, v10
	v_mul_f32_e32 v107, v11, v11
	v_mul_f32_e32 v108, v12, v12
	v_mul_f32_e32 v109, v13, v13
	v_mul_f32_e32 v110, v14, v14
	v_mul_f32_e32 v111, v15, v15
	v_mul_f32_e32 v112, v16, v16
	v_mul_f32_e32 v113, v17, v17
	v_mul_f32_e32 v114, v18, v18
	v_mul_f32_e32 v115, v19, v19
	v_fmac_f32_e32 v100, v20, v20
	v_fmac_f32_e32 v101, v21, v21
	v_fmac_f32_e32 v102, v22, v22
	v_fmac_f32_e32 v103, v23, v23
	v_fmac_f32_e32 v104, v24, v24
	v_fmac_f32_e32 v105, v25, v25
	v_fmac_f32_e32 v106, v26, v26
	v_fmac_f32_e32 v107, v27, v27
	v_fmac_f32_e32 v108, v28, v28
	v_fmac_f32_e32 v109, v29, v29
	v_fmac_f32_e32 v110, v30, v30
	v_fmac_f32_e32 v111, v31, v31
	v_fmac_f32_e32 v112, v32, v32
	v_fmac_f32_e32 v113, v33, v33
	v_fmac_f32_e32 v114, v34, v34
	v_fmac_f32_e32 v115, v35, v35
	v_add_f32_e32 v100, v100, v101
	v_add_f32_e32 v100, v100, v102
	v_add_f32_e32 v100, v100, v103
	v_add_f32_e32 v100, v100, v104
	v_add_f32_e32 v100, v100, v105
	v_add_f32_e32 v100, v100, v106
	v_add_f32_e32 v100, v100, v107
	v_add_f32_e32 v100, v100, v108
	v_add_f32_e32 v100, v100, v109
	v_add_f32_e32 v100, v100, v110
	v_add_f32_e32 v100, v100, v111
	v_add_f32_e32 v100, v100, v112
	v_add_f32_e32 v100, v100, v113
	v_add_f32_e32 v100, v100, v114
	v_add_f32_e32 v100, v100, v115
	v_mov_b32_e32 v101, v100
	s_nop 1
	v_permlane32_swap_b32_e32 v100, v101
	v_add_f32_e32 v100, v100, v101
	v_fmamk_f32 v100, v100, 0x3c800000, v159
	v_mul_f32_e32 v101, 0x4b800000, v100
	v_cmp_gt_f32_e32 vcc, s48, v100
	s_nop 1
	v_cndmask_b32_e32 v100, v100, v101, vcc
	v_rsq_f32_e32 v100, v100
	s_nop 0
	v_mul_f32_e32 v101, 0x45800000, v100
	v_cndmask_b32_e32 v100, v100, v101, vcc
	v_mul_f32_e32 v20, v20, v100
	v_mul_f32_e32 v21, v21, v100
	v_mul_f32_e32 v22, v22, v100
	v_mul_f32_e32 v23, v23, v100
	v_mul_f32_e32 v20, v20, v52
	v_mul_f32_e32 v21, v21, v53
	v_mul_f32_e32 v22, v22, v54
	v_mul_f32_e32 v23, v23, v55
	v_cvt_pk_bf16_f32 v20, v20, v21
	v_cvt_pk_bf16_f32 v21, v22, v23
	global_store_dwordx2 v[242:243], v[20:21], off
	v_mul_f32_e32 v24, v24, v100
	v_mul_f32_e32 v25, v25, v100
	v_mul_f32_e32 v26, v26, v100
	v_mul_f32_e32 v27, v27, v100
	v_mul_f32_e32 v24, v24, v56
	v_mul_f32_e32 v25, v25, v57
	v_mul_f32_e32 v26, v26, v58
	v_mul_f32_e32 v27, v27, v59
	v_cvt_pk_bf16_f32 v24, v24, v25
	v_cvt_pk_bf16_f32 v25, v26, v27
	global_store_dwordx2 v[242:243], v[24:25], off offset:16
	v_mul_f32_e32 v28, v28, v100
	v_mul_f32_e32 v29, v29, v100
	v_mul_f32_e32 v30, v30, v100
	v_mul_f32_e32 v31, v31, v100
	v_mul_f32_e32 v28, v28, v60
	v_mul_f32_e32 v29, v29, v61
	v_mul_f32_e32 v30, v30, v62
	v_mul_f32_e32 v31, v31, v63
	v_cvt_pk_bf16_f32 v28, v28, v29
	v_cvt_pk_bf16_f32 v29, v30, v31
	global_store_dwordx2 v[242:243], v[28:29], off offset:32
	v_mul_f32_e32 v32, v32, v100
	v_mul_f32_e32 v33, v33, v100
	v_mul_f32_e32 v34, v34, v100
	v_mul_f32_e32 v35, v35, v100
	v_mul_f32_e32 v32, v32, v64
	v_mul_f32_e32 v33, v33, v65
	v_mul_f32_e32 v34, v34, v66
	v_mul_f32_e32 v35, v35, v67
	v_cvt_pk_bf16_f32 v32, v32, v33
	v_cvt_pk_bf16_f32 v33, v34, v35
	global_store_dwordx2 v[242:243], v[32:33], off offset:48
	v_mul_f32_e32 v4, v4, v100
	v_mul_f32_e32 v5, v5, v100
	v_mul_f32_e32 v6, v6, v100
	v_mul_f32_e32 v7, v7, v100
	v_mul_f32_e32 v4, v4, v68
	v_mul_f32_e32 v5, v5, v69
	v_mul_f32_e32 v6, v6, v70
	v_mul_f32_e32 v7, v7, v71
	v_cvt_pk_bf16_f32 v4, v4, v5
	v_cvt_pk_bf16_f32 v5, v6, v7
	global_store_dwordx2 v[242:243], v[4:5], off offset:64
	v_mul_f32_e32 v8, v8, v100
	v_mul_f32_e32 v9, v9, v100
	v_mul_f32_e32 v10, v10, v100
	v_mul_f32_e32 v11, v11, v100
	v_mul_f32_e32 v8, v8, v72
	v_mul_f32_e32 v9, v9, v73
	v_mul_f32_e32 v10, v10, v74
	v_mul_f32_e32 v11, v11, v75
	v_cvt_pk_bf16_f32 v8, v8, v9
	v_cvt_pk_bf16_f32 v9, v10, v11
	global_store_dwordx2 v[242:243], v[8:9], off offset:80
	v_mul_f32_e32 v12, v12, v100
	v_mul_f32_e32 v13, v13, v100
	v_mul_f32_e32 v14, v14, v100
	v_mul_f32_e32 v15, v15, v100
	v_mul_f32_e32 v12, v12, v76
	v_mul_f32_e32 v13, v13, v77
	v_mul_f32_e32 v14, v14, v78
	v_mul_f32_e32 v15, v15, v79
	v_cvt_pk_bf16_f32 v12, v12, v13
	v_cvt_pk_bf16_f32 v13, v14, v15
	global_store_dwordx2 v[242:243], v[12:13], off offset:96
	v_mul_f32_e32 v16, v16, v100
	v_mul_f32_e32 v17, v17, v100
	v_mul_f32_e32 v18, v18, v100
	v_mul_f32_e32 v19, v19, v100
	v_mul_f32_e32 v16, v16, v80
	v_mul_f32_e32 v17, v17, v81
	v_mul_f32_e32 v18, v18, v82
	v_mul_f32_e32 v19, v19, v83
	v_cvt_pk_bf16_f32 v16, v16, v17
	v_cvt_pk_bf16_f32 v17, v18, v19
	global_store_dwordx2 v[242:243], v[16:17], off offset:112

.LBB0_637:
	s_or_b64 exec, exec, s[74:75]
	v_mov_b32_e32 v235, v3
	v_lshl_add_u64 v[228:229], v[228:229], 0, s[72:73]
	v_lshl_add_u64 v[230:231], v[230:231], 0, s[72:73]
	v_lshl_add_u64 v[232:233], v[232:233], 0, v[2:3]
	v_lshl_add_u64 v[236:237], v[236:237], 0, v[234:235]
	s_branch .LBB0_638
.Lq_claim_att:
	s_and_saveexec_b64 s[100:101], s[44:45]
	v_mov_b32_e32 v255, 1
	global_atomic_add v255, v3, v255, s[0:1] sc0
	s_mov_b64 exec, s[100:101]

.LBB0_659:
	s_and_saveexec_b64 s[100:101], s[44:45]
	v_mov_b32_e32 v255, 1
	global_atomic_add v255, v3, v255, s[0:1] sc0
	s_mov_b64 exec, s[100:101]
	v_mov_b32_e32 v4, v3
	v_mov_b32_e32 v5, v3
	v_mov_b32_e32 v6, v3
	v_mov_b32_e32 v7, v3
	v_mov_b32_e32 v8, v3
	v_mov_b32_e32 v9, v3
	v_mov_b32_e32 v10, v3
	v_mov_b32_e32 v11, v3
	v_mov_b32_e32 v12, v3
	v_mov_b32_e32 v13, v3
	v_mov_b32_e32 v14, v3
	v_mov_b32_e32 v15, v3
	v_mov_b32_e32 v16, v3
	v_mov_b32_e32 v17, v3
	v_mov_b32_e32 v18, v3
	v_mov_b32_e32 v19, v3
	v_mov_b32_e32 v20, v3
	v_mov_b32_e32 v21, v3
	v_mov_b32_e32 v22, v3
	v_mov_b32_e32 v23, v3
	v_mov_b32_e32 v24, v3
	v_mov_b32_e32 v25, v3
	v_mov_b32_e32 v26, v3
	v_mov_b32_e32 v27, v3
	v_mov_b32_e32 v28, v3
	v_mov_b32_e32 v29, v3
	v_mov_b32_e32 v30, v3
	v_mov_b32_e32 v31, v3
	v_mov_b32_e32 v32, v3
	v_mov_b32_e32 v33, v3
	v_mov_b32_e32 v2, v3
	v_mov_b64_e32 v[34:35], v[32:33]
	v_mov_b32_e32 v238, 0
	v_mov_b64_e32 v[32:33], v[30:31]
	v_mov_b64_e32 v[30:31], v[28:29]
	v_mov_b64_e32 v[28:29], v[26:27]
	v_mov_b64_e32 v[26:27], v[24:25]
	v_mov_b64_e32 v[24:25], v[22:23]
	v_mov_b64_e32 v[22:23], v[20:21]
	v_mov_b64_e32 v[20:21], v[18:19]
	v_mov_b64_e32 v[18:19], v[16:17]
	v_mov_b64_e32 v[16:17], v[14:15]
	v_mov_b64_e32 v[14:15], v[12:13]
	v_mov_b64_e32 v[12:13], v[10:11]
	v_mov_b64_e32 v[10:11], v[8:9]
	v_mov_b64_e32 v[8:9], v[6:7]
	v_mov_b64_e32 v[6:7], v[4:5]
	v_mov_b64_e32 v[4:5], v[2:3]
	s_branch .LBB0_590

	.amdhsa_kernel _Z14fwd_megakernel6Params
		.amdhsa_group_segment_fixed_size 0
		.amdhsa_private_segment_fixed_size 0
		.amdhsa_kernarg_size 392
		.amdhsa_user_sgpr_count 2
		.amdhsa_user_sgpr_dispatch_ptr 0
		.amdhsa_user_sgpr_queue_ptr 0
		.amdhsa_user_sgpr_kernarg_segment_ptr 1
		.amdhsa_user_sgpr_dispatch_id 0
		.amdhsa_user_sgpr_kernarg_preload_length 0
		.amdhsa_user_sgpr_kernarg_preload_offset 0
		.amdhsa_user_sgpr_private_segment_size 0
		.amdhsa_uses_dynamic_stack 0
		.amdhsa_enable_private_segment 0
		.amdhsa_system_sgpr_workgroup_id_x 1
		.amdhsa_system_sgpr_workgroup_id_y 0
		.amdhsa_system_sgpr_workgroup_id_z 0
		.amdhsa_system_sgpr_workgroup_info 0
		.amdhsa_system_vgpr_workitem_id 0
		.amdhsa_next_free_vgpr 256
		.amdhsa_next_free_sgpr 102
		.amdhsa_accum_offset 256
		.amdhsa_reserve_vcc 1
		.amdhsa_float_round_mode_32 0
		.amdhsa_float_round_mode_16_64 0
		.amdhsa_float_denorm_mode_32 3
		.amdhsa_float_denorm_mode_16_64 3
		.amdhsa_dx10_clamp 1
		.amdhsa_ieee_mode 1
		.amdhsa_fp16_overflow 0
		.amdhsa_tg_split 0
		.amdhsa_exception_fp_ieee_invalid_op 0
		.amdhsa_exception_fp_denorm_src 0
		.amdhsa_exception_fp_ieee_div_zero 0
		.amdhsa_exception_fp_ieee_overflow 0
		.amdhsa_exception_fp_ieee_underflow 0
		.amdhsa_exception_fp_ieee_inexact 0
		.amdhsa_exception_int_div_zero 0
	.end_amdhsa_kernel

amdhsa.kernels:
  - .agpr_count:     0
    .args:
      - .offset:         0
        .size:           136
        .value_kind:     by_value
      - .offset:         136
        .size:           4
        .value_kind:     hidden_block_count_x
      - .offset:         140
        .size:           4
        .value_kind:     hidden_block_count_y
      - .offset:         144
        .size:           4
        .value_kind:     hidden_block_count_z
      - .offset:         148
        .size:           2
        .value_kind:     hidden_group_size_x
      - .offset:         150
        .size:           2
        .value_kind:     hidden_group_size_y
      - .offset:         152
        .size:           2
        .value_kind:     hidden_group_size_z
      - .offset:         154
        .size:           2
        .value_kind:     hidden_remainder_x
      - .offset:         156
        .size:           2
        .value_kind:     hidden_remainder_y
      - .offset:         158
        .size:           2
        .value_kind:     hidden_remainder_z
      - .offset:         176
        .size:           8
        .value_kind:     hidden_global_offset_x
      - .offset:         184
        .size:           8
        .value_kind:     hidden_global_offset_y
      - .offset:         192
        .size:           8
        .value_kind:     hidden_global_offset_z
      - .offset:         200
        .size:           2
        .value_kind:     hidden_grid_dims
      - .offset:         256
        .size:           4
        .value_kind:     hidden_dynamic_lds_size
    .group_segment_fixed_size: 0
    .kernarg_segment_align: 8
    .kernarg_segment_size: 392
    .language:       OpenCL C
    .language_version:
      - 2
      - 0
    .max_flat_workgroup_size: 512
    .name:           _Z14fwd_megakernel6Params
    .private_segment_fixed_size: 0
    .sgpr_count:     108
    .sgpr_spill_count: 16
    .symbol:         _Z14fwd_megakernel6Params.kd
    .uniform_work_group_size: 1
    .uses_dynamic_stack: false
    .vgpr_count:     256
    .vgpr_spill_count: 0
    .wavefront_size: 64
